# P5 rewritten by hand (16-byte loads/stores per lane, two groups of 8 chain steps in flight) with plain write-back stores instead of write-through
# speedup vs baseline: 1.0062x; 1.0014x over previous
; __device__ __forceinline__ unsigned pk2(float lo, float hi) { const f32x2cv v = {lo, hi}; const bf16x2cv b = __builtin_convertvector(v, bf16x2cv); return __builtin_bit_cast(unsigned, b); }
; __global__ void __launch_bounds__(NT, 2) fwd_kernel(Args args) {
;     ...
;     {
;         PHASE_IDS
;         const int gt = bl * NT + tid;
;         if (gt < 65536) {
;             const int chain = gt >> 11, b = chain >> 3, h = (chain >> 1) & 3, d = chain & 1, e = 4 * (gt & 2047);
;             float s0 = 0.f, s1 = 0.f, s2 = 0.f, s3 = 0.f;
;             _Pragma("unroll 1") for (int st = 0; st < 72; st += 8) {
;                 v2u loc[8]; f32x4 dec[8]; bf16* ad[8];
; #pragma unroll
;                 for (int u = 0; u < 8; ++u) { const int ch = chain_chunk(b, d, (st + u < 68) ? st + u : 67); ad[u] = STG + (size_t)((ch * 4 + h) * 2 + d) * 8192 + e; loc[u] = *(const v2u*)ad[u];
;                     dec[u] = *(const f32x4*)(DECG + (size_t)(ch * 2 + d) * 256 + h * 64 + (e & 63)); }
; #pragma unroll
;                 for (int u = 0; u < 8; ++u) { if (st + u >= 68) break; v2u o; o.x = pk2(s0, s1); o.y = pk2(s2, s3); *(v2u*)ad[u] = o;
;                     s0 = s0 * dec[u].x + bflo(loc[u].x); s1 = s1 * dec[u].y + bfhi(loc[u].x); s2 = s2 * dec[u].z + bflo(loc[u].y); s3 = s3 * dec[u].w + bfhi(loc[u].y); }
;             }
;         } else {
;             const int g2 = gt - 65536, chain = g2 >> 10, b = chain >> 4, hh = (chain >> 1) & 7, d = chain & 1, e = 4 * (g2 & 1023);
.LBB0_675:
	s_or_b64 exec, exec, s[4:5]
	s_waitcnt lgkmcnt(0)
	v_mov_b32_e32 v1, v0
	s_barrier
	v_readfirstlane_b32 s52, v0
	v_and_b32_e32 v5, 63, v0
	v_mov_b32_e32 v3, 0
	s_lshr_b32 s52, s52, 6
	s_cmp_gt_u32 s52, 3
	s_cbranch_scc1 .LBB0_705
	s_lshl_b32 s53, s2, 2
	s_add_u32 s53, s53, s52
	v_lshlrev_b32_e32 v1, 4, v5
	v_and_b32_e32 v2, 7, v5
	v_lshlrev_b32_e32 v2, 5, v2
	s_cmp_lt_u32 s53, 0x200
	s_cbranch_scc0 .Lp5_ssd
	s_lshr_b32 s69, s53, 4
	s_and_b32 s70, s53, 15
	s_lshr_b32 s71, s69, 3
	s_bfe_u32 s72, s69, 0x20001
	s_and_b32 s73, s69, 1
	s_lshl_b32 s74, s72, 15
	s_lshl_b32 s75, s73, 14
	s_add_u32 s74, s74, s75
	s_lshl_b32 s75, s70, 10
	s_add_u32 s74, s74, s75
	s_add_u32 s80, s78, 0xb400000
	s_addc_u32 s81, s79, 0
	s_add_u32 s80, s80, s74
	s_addc_u32 s81, s81, 0
	s_lshl_b32 s74, s73, 10
	s_lshl_b32 s75, s72, 8
	s_add_u32 s74, s74, s75
	s_add_u32 s82, s78, 0xc20000
	s_addc_u32 s83, s79, 0
	s_add_u32 s82, s82, s74
	s_addc_u32 s83, s83, 0
	s_movk_i32 s84, 0x800
	s_branch .Lp5_common

; __device__ __forceinline__ unsigned pk2(float lo, float hi) { const f32x2cv v = {lo, hi}; const bf16x2cv b = __builtin_convertvector(v, bf16x2cv); return __builtin_bit_cast(unsigned, b); }
; __global__ void __launch_bounds__(NT, 2) fwd_kernel(Args args) {
;     ...
;             const int chain = gt >> 11, b = chain >> 3, h = (chain >> 1) & 3, d = chain & 1, e = 4 * (gt & 2047);
;             float s0 = 0.f, s1 = 0.f, s2 = 0.f, s3 = 0.f;
;             _Pragma("unroll 1") for (int st = 0; st < 72; st += 8) {
;                 v2u loc[8]; f32x4 dec[8]; bf16* ad[8];
; #pragma unroll
;                 for (int u = 0; u < 8; ++u) { const int ch = chain_chunk(b, d, (st + u < 68) ? st + u : 67); ad[u] = STG + (size_t)((ch * 4 + h) * 2 + d) * 8192 + e; loc[u] = *(const v2u*)ad[u];
;                     dec[u] = *(const f32x4*)(DECG + (size_t)(ch * 2 + d) * 256 + h * 64 + (e & 63)); }
; #pragma unroll
;                 for (int u = 0; u < 8; ++u) { if (st + u >= 68) break; v2u o; o.x = pk2(s0, s1); o.y = pk2(s2, s3); *(v2u*)ad[u] = o;
;                     s0 = s0 * dec[u].x + bflo(loc[u].x); s1 = s1 * dec[u].y + bfhi(loc[u].x); s2 = s2 * dec[u].z + bflo(loc[u].y); s3 = s3 * dec[u].w + bfhi(loc[u].y); }
.Lp5_fwd:
	s_cmp_eq_u32 s84, 0x40
	s_cbranch_scc1 .Lp5_ssd_main
	v_mov_b32_e32 v8, 0
	v_mov_b32_e32 v9, 0
	v_mov_b32_e32 v10, 0
	v_mov_b32_e32 v11, 0
	v_mov_b32_e32 v12, 0
	v_mov_b32_e32 v13, 0
	v_mov_b32_e32 v14, 0
	v_mov_b32_e32 v15, 0
	global_load_dwordx4 v[32:35], v1, s[54:55] nt
	global_load_dwordx4 v[64:67], v2, s[56:57]
	global_load_dwordx4 v[68:71], v2, s[56:57] offset:16
	s_add_u32 s54, s54, s60
	s_addc_u32 s55, s55, s61
	s_add_u32 s56, s56, s62
	s_addc_u32 s57, s57, s63
	global_load_dwordx4 v[36:39], v1, s[54:55] nt
	global_load_dwordx4 v[72:75], v2, s[56:57]
	global_load_dwordx4 v[76:79], v2, s[56:57] offset:16
	s_add_u32 s54, s54, s60
	s_addc_u32 s55, s55, s61
	s_add_u32 s56, s56, s62
	s_addc_u32 s57, s57, s63
	global_load_dwordx4 v[40:43], v1, s[54:55] nt
	global_load_dwordx4 v[80:83], v2, s[56:57]
	global_load_dwordx4 v[92:95], v2, s[56:57] offset:16
	s_add_u32 s54, s54, s60
	s_addc_u32 s55, s55, s61
	s_add_u32 s56, s56, s62
	s_addc_u32 s57, s57, s63
	global_load_dwordx4 v[44:47], v1, s[54:55] nt
	global_load_dwordx4 v[96:99], v2, s[56:57]
	global_load_dwordx4 v[100:103], v2, s[56:57] offset:16
	s_add_u32 s54, s54, s60
	s_addc_u32 s55, s55, s61
	s_add_u32 s56, s56, s62
	s_addc_u32 s57, s57, s63
	s_mov_b64 s[54:55], s[64:65]
	s_mov_b64 s[56:57], s[66:67]
	global_load_dwordx4 v[136:139], v1, s[54:55] nt
	global_load_dwordx4 v[168:171], v2, s[56:57]
	global_load_dwordx4 v[172:175], v2, s[56:57] offset:16
	s_add_u32 s54, s54, s60
	s_addc_u32 s55, s55, s61
	s_add_u32 s56, s56, s62
	s_addc_u32 s57, s57, s63
	global_load_dwordx4 v[140:143], v1, s[54:55] nt
	global_load_dwordx4 v[176:179], v2, s[56:57]
	global_load_dwordx4 v[180:183], v2, s[56:57] offset:16
	s_add_u32 s54, s54, s60
	s_addc_u32 s55, s55, s61
	s_add_u32 s56, s56, s62
	s_addc_u32 s57, s57, s63
	global_load_dwordx4 v[144:147], v1, s[54:55] nt
	global_load_dwordx4 v[184:187], v2, s[56:57]
	global_load_dwordx4 v[188:191], v2, s[56:57] offset:16
	s_add_u32 s54, s54, s60
	s_addc_u32 s55, s55, s61
	s_add_u32 s56, s56, s62
	s_addc_u32 s57, s57, s63
	global_load_dwordx4 v[148:151], v1, s[54:55] nt
	global_load_dwordx4 v[192:195], v2, s[56:57]
	global_load_dwordx4 v[196:199], v2, s[56:57] offset:16
	s_add_u32 s54, s54, s60
	s_addc_u32 s55, s55, s61
	s_add_u32 s56, s56, s62
	s_addc_u32 s57, s57, s63
	global_load_dwordx4 v[152:155], v1, s[54:55] nt
	global_load_dwordx4 v[200:203], v2, s[56:57]
	global_load_dwordx4 v[204:207], v2, s[56:57] offset:16
	s_add_u32 s54, s54, s60
	s_addc_u32 s55, s55, s61
	s_add_u32 s56, s56, s62
	s_addc_u32 s57, s57, s63
	global_load_dwordx4 v[156:159], v1, s[54:55] nt
	global_load_dwordx4 v[208:211], v2, s[56:57]
	global_load_dwordx4 v[212:215], v2, s[56:57] offset:16
	s_add_u32 s54, s54, s60
	s_addc_u32 s55, s55, s61
	s_add_u32 s56, s56, s62
	s_addc_u32 s57, s57, s63
	global_load_dwordx4 v[160:163], v1, s[54:55] nt
	global_load_dwordx4 v[216:219], v2, s[56:57]
	global_load_dwordx4 v[220:223], v2, s[56:57] offset:16
	s_add_u32 s54, s54, s60
	s_addc_u32 s55, s55, s61
	s_add_u32 s56, s56, s62
	s_addc_u32 s57, s57, s63
	global_load_dwordx4 v[164:167], v1, s[54:55] nt
	global_load_dwordx4 v[224:227], v2, s[56:57]
	global_load_dwordx4 v[228:231], v2, s[56:57] offset:16
	s_add_u32 s54, s54, s60
	s_addc_u32 s55, s55, s61
	s_add_u32 s56, s56, s62
	s_addc_u32 s57, s57, s63
	s_waitcnt vmcnt(33)
	v_cvt_pk_bf16_f32 v24, v8, v9
	v_cvt_pk_bf16_f32 v25, v10, v11
	v_cvt_pk_bf16_f32 v26, v12, v13
	v_cvt_pk_bf16_f32 v27, v14, v15
	global_store_dwordx4 v1, v[24:27], s[58:59]
	s_add_u32 s58, s58, s60
	s_addc_u32 s59, s59, s61
	v_lshlrev_b32_e32 v16, 16, v32
	v_and_b32_e32 v17, 0xffff0000, v32
	v_lshlrev_b32_e32 v18, 16, v33
	v_and_b32_e32 v19, 0xffff0000, v33
	v_lshlrev_b32_e32 v20, 16, v34
	v_and_b32_e32 v21, 0xffff0000, v34
	v_lshlrev_b32_e32 v22, 16, v35
	v_and_b32_e32 v23, 0xffff0000, v35
	v_fma_f32 v8, v8, v64, v16
	v_fma_f32 v9, v9, v65, v17
	v_fma_f32 v10, v10, v66, v18
	v_fma_f32 v11, v11, v67, v19
	v_fma_f32 v12, v12, v68, v20
	v_fma_f32 v13, v13, v69, v21
	v_fma_f32 v14, v14, v70, v22
	v_fma_f32 v15, v15, v71, v23
	s_waitcnt vmcnt(31)
	v_cvt_pk_bf16_f32 v28, v8, v9
	v_cvt_pk_bf16_f32 v29, v10, v11
	v_cvt_pk_bf16_f32 v30, v12, v13
	v_cvt_pk_bf16_f32 v31, v14, v15
	global_store_dwordx4 v1, v[28:31], s[58:59]
	s_add_u32 s58, s58, s60
	s_addc_u32 s59, s59, s61
	v_lshlrev_b32_e32 v16, 16, v36
	v_and_b32_e32 v17, 0xffff0000, v36
	v_lshlrev_b32_e32 v18, 16, v37
	v_and_b32_e32 v19, 0xffff0000, v37
	v_lshlrev_b32_e32 v20, 16, v38
	v_and_b32_e32 v21, 0xffff0000, v38
	v_lshlrev_b32_e32 v22, 16, v39
	v_and_b32_e32 v23, 0xffff0000, v39
	v_fma_f32 v8, v8, v72, v16
	v_fma_f32 v9, v9, v73, v17
	v_fma_f32 v10, v10, v74, v18
	v_fma_f32 v11, v11, v75, v19
	v_fma_f32 v12, v12, v76, v20
	v_fma_f32 v13, v13, v77, v21
	v_fma_f32 v14, v14, v78, v22
	v_fma_f32 v15, v15, v79, v23
	s_waitcnt vmcnt(29)
	v_cvt_pk_bf16_f32 v24, v8, v9
	v_cvt_pk_bf16_f32 v25, v10, v11
	v_cvt_pk_bf16_f32 v26, v12, v13
	v_cvt_pk_bf16_f32 v27, v14, v15
	global_store_dwordx4 v1, v[24:27], s[58:59]
	s_add_u32 s58, s58, s60
	s_addc_u32 s59, s59, s61
	v_lshlrev_b32_e32 v16, 16, v40
	v_and_b32_e32 v17, 0xffff0000, v40
	v_lshlrev_b32_e32 v18, 16, v41
	v_and_b32_e32 v19, 0xffff0000, v41
	v_lshlrev_b32_e32 v20, 16, v42
	v_and_b32_e32 v21, 0xffff0000, v42
	v_lshlrev_b32_e32 v22, 16, v43
	v_and_b32_e32 v23, 0xffff0000, v43
	v_fma_f32 v8, v8, v80, v16
	v_fma_f32 v9, v9, v81, v17
	v_fma_f32 v10, v10, v82, v18
	v_fma_f32 v11, v11, v83, v19
	v_fma_f32 v12, v12, v92, v20
	v_fma_f32 v13, v13, v93, v21
	v_fma_f32 v14, v14, v94, v22
	v_fma_f32 v15, v15, v95, v23
	s_waitcnt vmcnt(27)
	v_cvt_pk_bf16_f32 v28, v8, v9
	v_cvt_pk_bf16_f32 v29, v10, v11
	v_cvt_pk_bf16_f32 v30, v12, v13
	v_cvt_pk_bf16_f32 v31, v14, v15
	global_store_dwordx4 v1, v[28:31], s[58:59]
	s_add_u32 s58, s58, s60
	s_addc_u32 s59, s59, s61
	v_lshlrev_b32_e32 v16, 16, v44
	v_and_b32_e32 v17, 0xffff0000, v44
	v_lshlrev_b32_e32 v18, 16, v45
	v_and_b32_e32 v19, 0xffff0000, v45
	v_lshlrev_b32_e32 v20, 16, v46
	v_and_b32_e32 v21, 0xffff0000, v46
	v_lshlrev_b32_e32 v22, 16, v47
	v_and_b32_e32 v23, 0xffff0000, v47
	v_fma_f32 v8, v8, v96, v16
	v_fma_f32 v9, v9, v97, v17
	v_fma_f32 v10, v10, v98, v18
	v_fma_f32 v11, v11, v99, v19
	v_fma_f32 v12, v12, v100, v20
	v_fma_f32 v13, v13, v101, v21
	v_fma_f32 v14, v14, v102, v22
	v_fma_f32 v15, v15, v103, v23
	s_mov_b64 s[58:59], s[64:65]
	s_mov_b32 s68, 4
; __device__ __forceinline__ unsigned pk2(float lo, float hi) { const f32x2cv v = {lo, hi}; const bf16x2cv b = __builtin_convertvector(v, bf16x2cv); return __builtin_bit_cast(unsigned, b); }
; __global__ void __launch_bounds__(NT, 2) fwd_kernel(Args args) {
;     ...
;             _Pragma("unroll 1") for (int st = 0; st < 72; st += 8) {
;                 v2u loc[8]; f32x4 dec[8]; bf16* ad[8];
; #pragma unroll
;                 for (int u = 0; u < 8; ++u) { const int ch = chain_chunk(b, d, (st + u < 68) ? st + u : 67); ad[u] = STG + (size_t)((ch * 4 + h) * 2 + d) * 8192 + e; loc[u] = *(const v2u*)ad[u];
;                     dec[u] = *(const f32x4*)(DECG + (size_t)(ch * 2 + d) * 256 + h * 64 + (e & 63)); }
; #pragma unroll
;                 for (int u = 0; u < 8; ++u) { if (st + u >= 68) break; v2u o; o.x = pk2(s0, s1); o.y = pk2(s2, s3); *(v2u*)ad[u] = o;
;                     s0 = s0 * dec[u].x + bflo(loc[u].x); s1 = s1 * dec[u].y + bfhi(loc[u].x); s2 = s2 * dec[u].z + bflo(loc[u].y); s3 = s3 * dec[u].w + bfhi(loc[u].y); }
.Lp5_gla_loop:
	global_load_dwordx4 v[32:35], v1, s[54:55] nt
	global_load_dwordx4 v[64:67], v2, s[56:57]
	global_load_dwordx4 v[68:71], v2, s[56:57] offset:16
	s_add_u32 s54, s54, s60
	s_addc_u32 s55, s55, s61
	s_add_u32 s56, s56, s62
	s_addc_u32 s57, s57, s63
	global_load_dwordx4 v[36:39], v1, s[54:55] nt
	global_load_dwordx4 v[72:75], v2, s[56:57]
	global_load_dwordx4 v[76:79], v2, s[56:57] offset:16
	s_add_u32 s54, s54, s60
	s_addc_u32 s55, s55, s61
	s_add_u32 s56, s56, s62
	s_addc_u32 s57, s57, s63
	global_load_dwordx4 v[40:43], v1, s[54:55] nt
	global_load_dwordx4 v[80:83], v2, s[56:57]
	global_load_dwordx4 v[92:95], v2, s[56:57] offset:16
	s_add_u32 s54, s54, s60
	s_addc_u32 s55, s55, s61
	s_add_u32 s56, s56, s62
	s_addc_u32 s57, s57, s63
	global_load_dwordx4 v[44:47], v1, s[54:55] nt
	global_load_dwordx4 v[96:99], v2, s[56:57]
	global_load_dwordx4 v[100:103], v2, s[56:57] offset:16
	s_add_u32 s54, s54, s60
	s_addc_u32 s55, s55, s61
	s_add_u32 s56, s56, s62
	s_addc_u32 s57, s57, s63
	global_load_dwordx4 v[48:51], v1, s[54:55] nt
	global_load_dwordx4 v[104:107], v2, s[56:57]
	global_load_dwordx4 v[108:111], v2, s[56:57] offset:16
	s_add_u32 s54, s54, s60
	s_addc_u32 s55, s55, s61
	s_add_u32 s56, s56, s62
	s_addc_u32 s57, s57, s63
	global_load_dwordx4 v[52:55], v1, s[54:55] nt
	global_load_dwordx4 v[112:115], v2, s[56:57]
	global_load_dwordx4 v[116:119], v2, s[56:57] offset:16
	s_add_u32 s54, s54, s60
	s_addc_u32 s55, s55, s61
	s_add_u32 s56, s56, s62
	s_addc_u32 s57, s57, s63
	global_load_dwordx4 v[56:59], v1, s[54:55] nt
	global_load_dwordx4 v[120:123], v2, s[56:57]
	global_load_dwordx4 v[124:127], v2, s[56:57] offset:16
	s_add_u32 s54, s54, s60
	s_addc_u32 s55, s55, s61
	s_add_u32 s56, s56, s62
	s_addc_u32 s57, s57, s63
	global_load_dwordx4 v[60:63], v1, s[54:55] nt
	global_load_dwordx4 v[128:131], v2, s[56:57]
	global_load_dwordx4 v[132:135], v2, s[56:57] offset:16
	s_add_u32 s54, s54, s60
	s_addc_u32 s55, s55, s61
	s_add_u32 s56, s56, s62
	s_addc_u32 s57, s57, s63
	s_waitcnt vmcnt(49)
	v_cvt_pk_bf16_f32 v24, v8, v9
	v_cvt_pk_bf16_f32 v25, v10, v11
	v_cvt_pk_bf16_f32 v26, v12, v13
	v_cvt_pk_bf16_f32 v27, v14, v15
	global_store_dwordx4 v1, v[24:27], s[58:59]
	s_add_u32 s58, s58, s60
	s_addc_u32 s59, s59, s61
	v_lshlrev_b32_e32 v16, 16, v136
	v_and_b32_e32 v17, 0xffff0000, v136
	v_lshlrev_b32_e32 v18, 16, v137
	v_and_b32_e32 v19, 0xffff0000, v137
	v_lshlrev_b32_e32 v20, 16, v138
	v_and_b32_e32 v21, 0xffff0000, v138
	v_lshlrev_b32_e32 v22, 16, v139
	v_and_b32_e32 v23, 0xffff0000, v139
	v_fma_f32 v8, v8, v168, v16
	v_fma_f32 v9, v9, v169, v17
	v_fma_f32 v10, v10, v170, v18
	v_fma_f32 v11, v11, v171, v19
	v_fma_f32 v12, v12, v172, v20
	v_fma_f32 v13, v13, v173, v21
	v_fma_f32 v14, v14, v174, v22
	v_fma_f32 v15, v15, v175, v23
	s_waitcnt vmcnt(47)
	v_cvt_pk_bf16_f32 v28, v8, v9
	v_cvt_pk_bf16_f32 v29, v10, v11
	v_cvt_pk_bf16_f32 v30, v12, v13
	v_cvt_pk_bf16_f32 v31, v14, v15
	global_store_dwordx4 v1, v[28:31], s[58:59]
	s_add_u32 s58, s58, s60
	s_addc_u32 s59, s59, s61
	v_lshlrev_b32_e32 v16, 16, v140
	v_and_b32_e32 v17, 0xffff0000, v140
	v_lshlrev_b32_e32 v18, 16, v141
	v_and_b32_e32 v19, 0xffff0000, v141
	v_lshlrev_b32_e32 v20, 16, v142
	v_and_b32_e32 v21, 0xffff0000, v142
	v_lshlrev_b32_e32 v22, 16, v143
	v_and_b32_e32 v23, 0xffff0000, v143
	v_fma_f32 v8, v8, v176, v16
	v_fma_f32 v9, v9, v177, v17
	v_fma_f32 v10, v10, v178, v18
	v_fma_f32 v11, v11, v179, v19
	v_fma_f32 v12, v12, v180, v20
	v_fma_f32 v13, v13, v181, v21
	v_fma_f32 v14, v14, v182, v22
	v_fma_f32 v15, v15, v183, v23
	s_waitcnt vmcnt(45)
	v_cvt_pk_bf16_f32 v24, v8, v9
	v_cvt_pk_bf16_f32 v25, v10, v11
	v_cvt_pk_bf16_f32 v26, v12, v13
	v_cvt_pk_bf16_f32 v27, v14, v15
	global_store_dwordx4 v1, v[24:27], s[58:59]
	s_add_u32 s58, s58, s60
	s_addc_u32 s59, s59, s61
	v_lshlrev_b32_e32 v16, 16, v144
	v_and_b32_e32 v17, 0xffff0000, v144
	v_lshlrev_b32_e32 v18, 16, v145
	v_and_b32_e32 v19, 0xffff0000, v145
	v_lshlrev_b32_e32 v20, 16, v146
	v_and_b32_e32 v21, 0xffff0000, v146
	v_lshlrev_b32_e32 v22, 16, v147
	v_and_b32_e32 v23, 0xffff0000, v147
	v_fma_f32 v8, v8, v184, v16
	v_fma_f32 v9, v9, v185, v17
	v_fma_f32 v10, v10, v186, v18
	v_fma_f32 v11, v11, v187, v19
	v_fma_f32 v12, v12, v188, v20
	v_fma_f32 v13, v13, v189, v21
	v_fma_f32 v14, v14, v190, v22
	v_fma_f32 v15, v15, v191, v23
	s_waitcnt vmcnt(43)
	v_cvt_pk_bf16_f32 v28, v8, v9
	v_cvt_pk_bf16_f32 v29, v10, v11
	v_cvt_pk_bf16_f32 v30, v12, v13
	v_cvt_pk_bf16_f32 v31, v14, v15
	global_store_dwordx4 v1, v[28:31], s[58:59]
	s_add_u32 s58, s58, s60
	s_addc_u32 s59, s59, s61
	v_lshlrev_b32_e32 v16, 16, v148
	v_and_b32_e32 v17, 0xffff0000, v148
	v_lshlrev_b32_e32 v18, 16, v149
	v_and_b32_e32 v19, 0xffff0000, v149
	v_lshlrev_b32_e32 v20, 16, v150
	v_and_b32_e32 v21, 0xffff0000, v150
	v_lshlrev_b32_e32 v22, 16, v151
	v_and_b32_e32 v23, 0xffff0000, v151
	v_fma_f32 v8, v8, v192, v16
	v_fma_f32 v9, v9, v193, v17
	v_fma_f32 v10, v10, v194, v18
	v_fma_f32 v11, v11, v195, v19
	v_fma_f32 v12, v12, v196, v20
	v_fma_f32 v13, v13, v197, v21
	v_fma_f32 v14, v14, v198, v22
	v_fma_f32 v15, v15, v199, v23
	s_waitcnt vmcnt(41)
	v_cvt_pk_bf16_f32 v24, v8, v9
	v_cvt_pk_bf16_f32 v25, v10, v11
	v_cvt_pk_bf16_f32 v26, v12, v13
	v_cvt_pk_bf16_f32 v27, v14, v15
	global_store_dwordx4 v1, v[24:27], s[58:59]
	s_add_u32 s58, s58, s60
	s_addc_u32 s59, s59, s61
	v_lshlrev_b32_e32 v16, 16, v152
	v_and_b32_e32 v17, 0xffff0000, v152
	v_lshlrev_b32_e32 v18, 16, v153
	v_and_b32_e32 v19, 0xffff0000, v153
	v_lshlrev_b32_e32 v20, 16, v154
	v_and_b32_e32 v21, 0xffff0000, v154
	v_lshlrev_b32_e32 v22, 16, v155
	v_and_b32_e32 v23, 0xffff0000, v155
	v_fma_f32 v8, v8, v200, v16
	v_fma_f32 v9, v9, v201, v17
	v_fma_f32 v10, v10, v202, v18
	v_fma_f32 v11, v11, v203, v19
	v_fma_f32 v12, v12, v204, v20
	v_fma_f32 v13, v13, v205, v21
	v_fma_f32 v14, v14, v206, v22
	v_fma_f32 v15, v15, v207, v23
	s_waitcnt vmcnt(39)
; __device__ __forceinline__ unsigned pk2(float lo, float hi) { const f32x2cv v = {lo, hi}; const bf16x2cv b = __builtin_convertvector(v, bf16x2cv); return __builtin_bit_cast(unsigned, b); }
; __global__ void __launch_bounds__(NT, 2) fwd_kernel(Args args) {
;     ...
;             _Pragma("unroll 1") for (int st = 0; st < 72; st += 8) {
;                 v2u loc[8]; f32x4 dec[8]; bf16* ad[8];
; #pragma unroll
;                 for (int u = 0; u < 8; ++u) { const int ch = chain_chunk(b, d, (st + u < 68) ? st + u : 67); ad[u] = STG + (size_t)((ch * 4 + h) * 2 + d) * 8192 + e; loc[u] = *(const v2u*)ad[u];
;                     dec[u] = *(const f32x4*)(DECG + (size_t)(ch * 2 + d) * 256 + h * 64 + (e & 63)); }
; #pragma unroll
;                 for (int u = 0; u < 8; ++u) { if (st + u >= 68) break; v2u o; o.x = pk2(s0, s1); o.y = pk2(s2, s3); *(v2u*)ad[u] = o;
;                     s0 = s0 * dec[u].x + bflo(loc[u].x); s1 = s1 * dec[u].y + bfhi(loc[u].x); s2 = s2 * dec[u].z + bflo(loc[u].y); s3 = s3 * dec[u].w + bfhi(loc[u].y); }
	v_cvt_pk_bf16_f32 v28, v8, v9
	v_cvt_pk_bf16_f32 v29, v10, v11
	v_cvt_pk_bf16_f32 v30, v12, v13
	v_cvt_pk_bf16_f32 v31, v14, v15
	global_store_dwordx4 v1, v[28:31], s[58:59]
	s_add_u32 s58, s58, s60
	s_addc_u32 s59, s59, s61
	v_lshlrev_b32_e32 v16, 16, v156
	v_and_b32_e32 v17, 0xffff0000, v156
	v_lshlrev_b32_e32 v18, 16, v157
	v_and_b32_e32 v19, 0xffff0000, v157
	v_lshlrev_b32_e32 v20, 16, v158
	v_and_b32_e32 v21, 0xffff0000, v158
	v_lshlrev_b32_e32 v22, 16, v159
	v_and_b32_e32 v23, 0xffff0000, v159
	v_fma_f32 v8, v8, v208, v16
	v_fma_f32 v9, v9, v209, v17
	v_fma_f32 v10, v10, v210, v18
	v_fma_f32 v11, v11, v211, v19
	v_fma_f32 v12, v12, v212, v20
	v_fma_f32 v13, v13, v213, v21
	v_fma_f32 v14, v14, v214, v22
	v_fma_f32 v15, v15, v215, v23
	s_waitcnt vmcnt(37)
	v_cvt_pk_bf16_f32 v24, v8, v9
	v_cvt_pk_bf16_f32 v25, v10, v11
	v_cvt_pk_bf16_f32 v26, v12, v13
	v_cvt_pk_bf16_f32 v27, v14, v15
	global_store_dwordx4 v1, v[24:27], s[58:59]
	s_add_u32 s58, s58, s60
	s_addc_u32 s59, s59, s61
	v_lshlrev_b32_e32 v16, 16, v160
	v_and_b32_e32 v17, 0xffff0000, v160
	v_lshlrev_b32_e32 v18, 16, v161
	v_and_b32_e32 v19, 0xffff0000, v161
	v_lshlrev_b32_e32 v20, 16, v162
	v_and_b32_e32 v21, 0xffff0000, v162
	v_lshlrev_b32_e32 v22, 16, v163
	v_and_b32_e32 v23, 0xffff0000, v163
	v_fma_f32 v8, v8, v216, v16
	v_fma_f32 v9, v9, v217, v17
	v_fma_f32 v10, v10, v218, v18
	v_fma_f32 v11, v11, v219, v19
	v_fma_f32 v12, v12, v220, v20
	v_fma_f32 v13, v13, v221, v21
	v_fma_f32 v14, v14, v222, v22
	v_fma_f32 v15, v15, v223, v23
	s_waitcnt vmcnt(35)
	v_cvt_pk_bf16_f32 v28, v8, v9
	v_cvt_pk_bf16_f32 v29, v10, v11
	v_cvt_pk_bf16_f32 v30, v12, v13
	v_cvt_pk_bf16_f32 v31, v14, v15
	global_store_dwordx4 v1, v[28:31], s[58:59]
	s_add_u32 s58, s58, s60
	s_addc_u32 s59, s59, s61
	v_lshlrev_b32_e32 v16, 16, v164
	v_and_b32_e32 v17, 0xffff0000, v164
	v_lshlrev_b32_e32 v18, 16, v165
	v_and_b32_e32 v19, 0xffff0000, v165
	v_lshlrev_b32_e32 v20, 16, v166
	v_and_b32_e32 v21, 0xffff0000, v166
	v_lshlrev_b32_e32 v22, 16, v167
	v_and_b32_e32 v23, 0xffff0000, v167
	v_fma_f32 v8, v8, v224, v16
	v_fma_f32 v9, v9, v225, v17
	v_fma_f32 v10, v10, v226, v18
	v_fma_f32 v11, v11, v227, v19
	v_fma_f32 v12, v12, v228, v20
	v_fma_f32 v13, v13, v229, v21
	v_fma_f32 v14, v14, v230, v22
	v_fma_f32 v15, v15, v231, v23
	global_load_dwordx4 v[136:139], v1, s[54:55] nt
	global_load_dwordx4 v[168:171], v2, s[56:57]
	global_load_dwordx4 v[172:175], v2, s[56:57] offset:16
	s_add_u32 s54, s54, s60
	s_addc_u32 s55, s55, s61
	s_add_u32 s56, s56, s62
	s_addc_u32 s57, s57, s63
	global_load_dwordx4 v[140:143], v1, s[54:55] nt
	global_load_dwordx4 v[176:179], v2, s[56:57]
	global_load_dwordx4 v[180:183], v2, s[56:57] offset:16
	s_add_u32 s54, s54, s60
	s_addc_u32 s55, s55, s61
	s_add_u32 s56, s56, s62
	s_addc_u32 s57, s57, s63
	global_load_dwordx4 v[144:147], v1, s[54:55] nt
	global_load_dwordx4 v[184:187], v2, s[56:57]
	global_load_dwordx4 v[188:191], v2, s[56:57] offset:16
	s_add_u32 s54, s54, s60
	s_addc_u32 s55, s55, s61
	s_add_u32 s56, s56, s62
	s_addc_u32 s57, s57, s63
	global_load_dwordx4 v[148:151], v1, s[54:55] nt
	global_load_dwordx4 v[192:195], v2, s[56:57]
	global_load_dwordx4 v[196:199], v2, s[56:57] offset:16
	s_add_u32 s54, s54, s60
	s_addc_u32 s55, s55, s61
	s_add_u32 s56, s56, s62
	s_addc_u32 s57, s57, s63
	global_load_dwordx4 v[152:155], v1, s[54:55] nt
	global_load_dwordx4 v[200:203], v2, s[56:57]
	global_load_dwordx4 v[204:207], v2, s[56:57] offset:16
	s_add_u32 s54, s54, s60
	s_addc_u32 s55, s55, s61
	s_add_u32 s56, s56, s62
	s_addc_u32 s57, s57, s63
	global_load_dwordx4 v[156:159], v1, s[54:55] nt
	global_load_dwordx4 v[208:211], v2, s[56:57]
	global_load_dwordx4 v[212:215], v2, s[56:57] offset:16
	s_add_u32 s54, s54, s60
	s_addc_u32 s55, s55, s61
	s_add_u32 s56, s56, s62
	s_addc_u32 s57, s57, s63
	global_load_dwordx4 v[160:163], v1, s[54:55] nt
	global_load_dwordx4 v[216:219], v2, s[56:57]
	global_load_dwordx4 v[220:223], v2, s[56:57] offset:16
	s_add_u32 s54, s54, s60
	s_addc_u32 s55, s55, s61
	s_add_u32 s56, s56, s62
	s_addc_u32 s57, s57, s63
	global_load_dwordx4 v[164:167], v1, s[54:55] nt
	global_load_dwordx4 v[224:227], v2, s[56:57]
	global_load_dwordx4 v[228:231], v2, s[56:57] offset:16
	s_add_u32 s54, s54, s60
	s_addc_u32 s55, s55, s61
	s_add_u32 s56, s56, s62
	s_addc_u32 s57, s57, s63
	s_waitcnt vmcnt(49)
	v_cvt_pk_bf16_f32 v24, v8, v9
	v_cvt_pk_bf16_f32 v25, v10, v11
	v_cvt_pk_bf16_f32 v26, v12, v13
	v_cvt_pk_bf16_f32 v27, v14, v15
	global_store_dwordx4 v1, v[24:27], s[58:59]
	s_add_u32 s58, s58, s60
	s_addc_u32 s59, s59, s61
	v_lshlrev_b32_e32 v16, 16, v32
	v_and_b32_e32 v17, 0xffff0000, v32
	v_lshlrev_b32_e32 v18, 16, v33
	v_and_b32_e32 v19, 0xffff0000, v33
	v_lshlrev_b32_e32 v20, 16, v34
	v_and_b32_e32 v21, 0xffff0000, v34
	v_lshlrev_b32_e32 v22, 16, v35
	v_and_b32_e32 v23, 0xffff0000, v35
	v_fma_f32 v8, v8, v64, v16
	v_fma_f32 v9, v9, v65, v17
	v_fma_f32 v10, v10, v66, v18
	v_fma_f32 v11, v11, v67, v19
	v_fma_f32 v12, v12, v68, v20
	v_fma_f32 v13, v13, v69, v21
	v_fma_f32 v14, v14, v70, v22
	v_fma_f32 v15, v15, v71, v23
	s_waitcnt vmcnt(47)
	v_cvt_pk_bf16_f32 v28, v8, v9
	v_cvt_pk_bf16_f32 v29, v10, v11
	v_cvt_pk_bf16_f32 v30, v12, v13
	v_cvt_pk_bf16_f32 v31, v14, v15
	global_store_dwordx4 v1, v[28:31], s[58:59]
	s_add_u32 s58, s58, s60
	s_addc_u32 s59, s59, s61
	v_lshlrev_b32_e32 v16, 16, v36
	v_and_b32_e32 v17, 0xffff0000, v36
	v_lshlrev_b32_e32 v18, 16, v37
	v_and_b32_e32 v19, 0xffff0000, v37
	v_lshlrev_b32_e32 v20, 16, v38
	v_and_b32_e32 v21, 0xffff0000, v38
	v_lshlrev_b32_e32 v22, 16, v39
	v_and_b32_e32 v23, 0xffff0000, v39
	v_fma_f32 v8, v8, v72, v16
	v_fma_f32 v9, v9, v73, v17
	v_fma_f32 v10, v10, v74, v18
	v_fma_f32 v11, v11, v75, v19
	v_fma_f32 v12, v12, v76, v20
	v_fma_f32 v13, v13, v77, v21
	v_fma_f32 v14, v14, v78, v22
	v_fma_f32 v15, v15, v79, v23
	s_waitcnt vmcnt(45)
; __device__ __forceinline__ unsigned pk2(float lo, float hi) { const f32x2cv v = {lo, hi}; const bf16x2cv b = __builtin_convertvector(v, bf16x2cv); return __builtin_bit_cast(unsigned, b); }
; __global__ void __launch_bounds__(NT, 2) fwd_kernel(Args args) {
;     ...
;             _Pragma("unroll 1") for (int st = 0; st < 72; st += 8) {
;                 v2u loc[8]; f32x4 dec[8]; bf16* ad[8];
; #pragma unroll
;                 for (int u = 0; u < 8; ++u) { const int ch = chain_chunk(b, d, (st + u < 68) ? st + u : 67); ad[u] = STG + (size_t)((ch * 4 + h) * 2 + d) * 8192 + e; loc[u] = *(const v2u*)ad[u];
;                     dec[u] = *(const f32x4*)(DECG + (size_t)(ch * 2 + d) * 256 + h * 64 + (e & 63)); }
; #pragma unroll
;                 for (int u = 0; u < 8; ++u) { if (st + u >= 68) break; v2u o; o.x = pk2(s0, s1); o.y = pk2(s2, s3); *(v2u*)ad[u] = o;
;                     s0 = s0 * dec[u].x + bflo(loc[u].x); s1 = s1 * dec[u].y + bfhi(loc[u].x); s2 = s2 * dec[u].z + bflo(loc[u].y); s3 = s3 * dec[u].w + bfhi(loc[u].y); }
	v_cvt_pk_bf16_f32 v24, v8, v9
	v_cvt_pk_bf16_f32 v25, v10, v11
	v_cvt_pk_bf16_f32 v26, v12, v13
	v_cvt_pk_bf16_f32 v27, v14, v15
	global_store_dwordx4 v1, v[24:27], s[58:59]
	s_add_u32 s58, s58, s60
	s_addc_u32 s59, s59, s61
	v_lshlrev_b32_e32 v16, 16, v40
	v_and_b32_e32 v17, 0xffff0000, v40
	v_lshlrev_b32_e32 v18, 16, v41
	v_and_b32_e32 v19, 0xffff0000, v41
	v_lshlrev_b32_e32 v20, 16, v42
	v_and_b32_e32 v21, 0xffff0000, v42
	v_lshlrev_b32_e32 v22, 16, v43
	v_and_b32_e32 v23, 0xffff0000, v43
	v_fma_f32 v8, v8, v80, v16
	v_fma_f32 v9, v9, v81, v17
	v_fma_f32 v10, v10, v82, v18
	v_fma_f32 v11, v11, v83, v19
	v_fma_f32 v12, v12, v92, v20
	v_fma_f32 v13, v13, v93, v21
	v_fma_f32 v14, v14, v94, v22
	v_fma_f32 v15, v15, v95, v23
	s_waitcnt vmcnt(43)
	v_cvt_pk_bf16_f32 v28, v8, v9
	v_cvt_pk_bf16_f32 v29, v10, v11
	v_cvt_pk_bf16_f32 v30, v12, v13
	v_cvt_pk_bf16_f32 v31, v14, v15
	global_store_dwordx4 v1, v[28:31], s[58:59]
	s_add_u32 s58, s58, s60
	s_addc_u32 s59, s59, s61
	v_lshlrev_b32_e32 v16, 16, v44
	v_and_b32_e32 v17, 0xffff0000, v44
	v_lshlrev_b32_e32 v18, 16, v45
	v_and_b32_e32 v19, 0xffff0000, v45
	v_lshlrev_b32_e32 v20, 16, v46
	v_and_b32_e32 v21, 0xffff0000, v46
	v_lshlrev_b32_e32 v22, 16, v47
	v_and_b32_e32 v23, 0xffff0000, v47
	v_fma_f32 v8, v8, v96, v16
	v_fma_f32 v9, v9, v97, v17
	v_fma_f32 v10, v10, v98, v18
	v_fma_f32 v11, v11, v99, v19
	v_fma_f32 v12, v12, v100, v20
	v_fma_f32 v13, v13, v101, v21
	v_fma_f32 v14, v14, v102, v22
	v_fma_f32 v15, v15, v103, v23
	s_waitcnt vmcnt(41)
	v_cvt_pk_bf16_f32 v24, v8, v9
	v_cvt_pk_bf16_f32 v25, v10, v11
	v_cvt_pk_bf16_f32 v26, v12, v13
	v_cvt_pk_bf16_f32 v27, v14, v15
	global_store_dwordx4 v1, v[24:27], s[58:59]
	s_add_u32 s58, s58, s60
	s_addc_u32 s59, s59, s61
	v_lshlrev_b32_e32 v16, 16, v48
	v_and_b32_e32 v17, 0xffff0000, v48
	v_lshlrev_b32_e32 v18, 16, v49
	v_and_b32_e32 v19, 0xffff0000, v49
	v_lshlrev_b32_e32 v20, 16, v50
	v_and_b32_e32 v21, 0xffff0000, v50
	v_lshlrev_b32_e32 v22, 16, v51
	v_and_b32_e32 v23, 0xffff0000, v51
	v_fma_f32 v8, v8, v104, v16
	v_fma_f32 v9, v9, v105, v17
	v_fma_f32 v10, v10, v106, v18
	v_fma_f32 v11, v11, v107, v19
	v_fma_f32 v12, v12, v108, v20
	v_fma_f32 v13, v13, v109, v21
	v_fma_f32 v14, v14, v110, v22
	v_fma_f32 v15, v15, v111, v23
	s_waitcnt vmcnt(39)
	v_cvt_pk_bf16_f32 v28, v8, v9
	v_cvt_pk_bf16_f32 v29, v10, v11
	v_cvt_pk_bf16_f32 v30, v12, v13
	v_cvt_pk_bf16_f32 v31, v14, v15
	global_store_dwordx4 v1, v[28:31], s[58:59]
	s_add_u32 s58, s58, s60
	s_addc_u32 s59, s59, s61
	v_lshlrev_b32_e32 v16, 16, v52
	v_and_b32_e32 v17, 0xffff0000, v52
	v_lshlrev_b32_e32 v18, 16, v53
	v_and_b32_e32 v19, 0xffff0000, v53
	v_lshlrev_b32_e32 v20, 16, v54
	v_and_b32_e32 v21, 0xffff0000, v54
	v_lshlrev_b32_e32 v22, 16, v55
	v_and_b32_e32 v23, 0xffff0000, v55
	v_fma_f32 v8, v8, v112, v16
	v_fma_f32 v9, v9, v113, v17
	v_fma_f32 v10, v10, v114, v18
	v_fma_f32 v11, v11, v115, v19
	v_fma_f32 v12, v12, v116, v20
	v_fma_f32 v13, v13, v117, v21
	v_fma_f32 v14, v14, v118, v22
	v_fma_f32 v15, v15, v119, v23
	s_waitcnt vmcnt(37)
	v_cvt_pk_bf16_f32 v24, v8, v9
	v_cvt_pk_bf16_f32 v25, v10, v11
	v_cvt_pk_bf16_f32 v26, v12, v13
	v_cvt_pk_bf16_f32 v27, v14, v15
	global_store_dwordx4 v1, v[24:27], s[58:59]
	s_add_u32 s58, s58, s60
	s_addc_u32 s59, s59, s61
	v_lshlrev_b32_e32 v16, 16, v56
	v_and_b32_e32 v17, 0xffff0000, v56
	v_lshlrev_b32_e32 v18, 16, v57
	v_and_b32_e32 v19, 0xffff0000, v57
	v_lshlrev_b32_e32 v20, 16, v58
	v_and_b32_e32 v21, 0xffff0000, v58
	v_lshlrev_b32_e32 v22, 16, v59
	v_and_b32_e32 v23, 0xffff0000, v59
	v_fma_f32 v8, v8, v120, v16
	v_fma_f32 v9, v9, v121, v17
	v_fma_f32 v10, v10, v122, v18
	v_fma_f32 v11, v11, v123, v19
	v_fma_f32 v12, v12, v124, v20
	v_fma_f32 v13, v13, v125, v21
	v_fma_f32 v14, v14, v126, v22
	v_fma_f32 v15, v15, v127, v23
	s_waitcnt vmcnt(35)
	v_cvt_pk_bf16_f32 v28, v8, v9
	v_cvt_pk_bf16_f32 v29, v10, v11
	v_cvt_pk_bf16_f32 v30, v12, v13
	v_cvt_pk_bf16_f32 v31, v14, v15
	global_store_dwordx4 v1, v[28:31], s[58:59]
	s_add_u32 s58, s58, s60
	s_addc_u32 s59, s59, s61
	v_lshlrev_b32_e32 v16, 16, v60
	v_and_b32_e32 v17, 0xffff0000, v60
	v_lshlrev_b32_e32 v18, 16, v61
	v_and_b32_e32 v19, 0xffff0000, v61
	v_lshlrev_b32_e32 v20, 16, v62
	v_and_b32_e32 v21, 0xffff0000, v62
	v_lshlrev_b32_e32 v22, 16, v63
	v_and_b32_e32 v23, 0xffff0000, v63
	v_fma_f32 v8, v8, v128, v16
	v_fma_f32 v9, v9, v129, v17
	v_fma_f32 v10, v10, v130, v18
	v_fma_f32 v11, v11, v131, v19
	v_fma_f32 v12, v12, v132, v20
	v_fma_f32 v13, v13, v133, v21
	v_fma_f32 v14, v14, v134, v22
	v_fma_f32 v15, v15, v135, v23
	s_sub_u32 s68, s68, 1
	s_cmp_lg_u32 s68, 0
	s_cbranch_scc1 .Lp5_gla_loop
	s_branch .LBB0_705
; __device__ __forceinline__ unsigned pk2(float lo, float hi) { const f32x2cv v = {lo, hi}; const bf16x2cv b = __builtin_convertvector(v, bf16x2cv); return __builtin_bit_cast(unsigned, b); }
; __global__ void __launch_bounds__(NT, 2) fwd_kernel(Args args) {
;     ...
;             const int g2 = gt - 65536, chain = g2 >> 10, b = chain >> 4, hh = (chain >> 1) & 7, d = chain & 1, e = 4 * (g2 & 1023);
;             float s0 = 0.f, s1 = 0.f, s2 = 0.f, s3 = 0.f;
;             _Pragma("unroll 1") for (int st = 0; st < 72; st += 8) {
;                 v2u loc[8]; float dec[8]; bf16* ad[8];
; #pragma unroll
;                 for (int u = 0; u < 8; ++u) { const int ch = chain_chunk(b, d, (st + u < 68) ? st + u : 67); ad[u] = STS + (size_t)((ch * 8 + hh) * 2 + d) * 4096 + e; loc[u] = *(const v2u*)ad[u];
;                     dec[u] = DECS[(size_t)(ch * 2 + d) * 8 + hh]; }
; #pragma unroll
;                 for (int u = 0; u < 8; ++u) { if (st + u >= 68) break; v2u o; o.x = pk2(s0, s1); o.y = pk2(s2, s3); *(v2u*)ad[u] = o;
;                     s0 = s0 * dec[u] + bflo(loc[u].x); s1 = s1 * dec[u] + bfhi(loc[u].x); s2 = s2 * dec[u] + bflo(loc[u].y); s3 = s3 * dec[u] + bfhi(loc[u].y); }
.Lp5_ssd_main:
	v_mov_b32_e32 v8, 0
	v_mov_b32_e32 v9, 0
	v_mov_b32_e32 v10, 0
	v_mov_b32_e32 v11, 0
	v_mov_b32_e32 v12, 0
	v_mov_b32_e32 v13, 0
	v_mov_b32_e32 v14, 0
	v_mov_b32_e32 v15, 0
	global_load_dwordx4 v[32:35], v1, s[54:55] nt
	global_load_dword v64, v3, s[56:57]
	s_add_u32 s54, s54, s60
	s_addc_u32 s55, s55, s61
	s_add_u32 s56, s56, s62
	s_addc_u32 s57, s57, s63
	global_load_dwordx4 v[36:39], v1, s[54:55] nt
	global_load_dword v72, v3, s[56:57]
	s_add_u32 s54, s54, s60
	s_addc_u32 s55, s55, s61
	s_add_u32 s56, s56, s62
	s_addc_u32 s57, s57, s63
	global_load_dwordx4 v[40:43], v1, s[54:55] nt
	global_load_dword v80, v3, s[56:57]
	s_add_u32 s54, s54, s60
	s_addc_u32 s55, s55, s61
	s_add_u32 s56, s56, s62
	s_addc_u32 s57, s57, s63
	global_load_dwordx4 v[44:47], v1, s[54:55] nt
	global_load_dword v96, v3, s[56:57]
	s_add_u32 s54, s54, s60
	s_addc_u32 s55, s55, s61
	s_add_u32 s56, s56, s62
	s_addc_u32 s57, s57, s63
	s_mov_b64 s[54:55], s[64:65]
	s_mov_b64 s[56:57], s[66:67]
	global_load_dwordx4 v[136:139], v1, s[54:55] nt
	global_load_dword v168, v3, s[56:57]
	s_add_u32 s54, s54, s60
	s_addc_u32 s55, s55, s61
	s_add_u32 s56, s56, s62
	s_addc_u32 s57, s57, s63
	global_load_dwordx4 v[140:143], v1, s[54:55] nt
	global_load_dword v176, v3, s[56:57]
	s_add_u32 s54, s54, s60
	s_addc_u32 s55, s55, s61
	s_add_u32 s56, s56, s62
	s_addc_u32 s57, s57, s63
	global_load_dwordx4 v[144:147], v1, s[54:55] nt
	global_load_dword v184, v3, s[56:57]
	s_add_u32 s54, s54, s60
	s_addc_u32 s55, s55, s61
	s_add_u32 s56, s56, s62
	s_addc_u32 s57, s57, s63
	global_load_dwordx4 v[148:151], v1, s[54:55] nt
	global_load_dword v192, v3, s[56:57]
	s_add_u32 s54, s54, s60
	s_addc_u32 s55, s55, s61
	s_add_u32 s56, s56, s62
	s_addc_u32 s57, s57, s63
	global_load_dwordx4 v[152:155], v1, s[54:55] nt
	global_load_dword v200, v3, s[56:57]
	s_add_u32 s54, s54, s60
	s_addc_u32 s55, s55, s61
	s_add_u32 s56, s56, s62
	s_addc_u32 s57, s57, s63
	global_load_dwordx4 v[156:159], v1, s[54:55] nt
	global_load_dword v208, v3, s[56:57]
	s_add_u32 s54, s54, s60
	s_addc_u32 s55, s55, s61
	s_add_u32 s56, s56, s62
	s_addc_u32 s57, s57, s63
	global_load_dwordx4 v[160:163], v1, s[54:55] nt
	global_load_dword v216, v3, s[56:57]
	s_add_u32 s54, s54, s60
	s_addc_u32 s55, s55, s61
	s_add_u32 s56, s56, s62
	s_addc_u32 s57, s57, s63
	global_load_dwordx4 v[164:167], v1, s[54:55] nt
	global_load_dword v224, v3, s[56:57]
	s_add_u32 s54, s54, s60
	s_addc_u32 s55, s55, s61
	s_add_u32 s56, s56, s62
	s_addc_u32 s57, s57, s63
	s_waitcnt vmcnt(22)
	v_cvt_pk_bf16_f32 v24, v8, v9
	v_cvt_pk_bf16_f32 v25, v10, v11
	v_cvt_pk_bf16_f32 v26, v12, v13
	v_cvt_pk_bf16_f32 v27, v14, v15
	global_store_dwordx4 v1, v[24:27], s[58:59]
	s_add_u32 s58, s58, s60
	s_addc_u32 s59, s59, s61
	v_lshlrev_b32_e32 v16, 16, v32
	v_and_b32_e32 v17, 0xffff0000, v32
	v_lshlrev_b32_e32 v18, 16, v33
	v_and_b32_e32 v19, 0xffff0000, v33
	v_lshlrev_b32_e32 v20, 16, v34
	v_and_b32_e32 v21, 0xffff0000, v34
	v_lshlrev_b32_e32 v22, 16, v35
	v_and_b32_e32 v23, 0xffff0000, v35
	v_fma_f32 v8, v8, v64, v16
	v_fma_f32 v9, v9, v64, v17
	v_fma_f32 v10, v10, v64, v18
	v_fma_f32 v11, v11, v64, v19
	v_fma_f32 v12, v12, v64, v20
	v_fma_f32 v13, v13, v64, v21
	v_fma_f32 v14, v14, v64, v22
	v_fma_f32 v15, v15, v64, v23
	s_waitcnt vmcnt(21)
	v_cvt_pk_bf16_f32 v28, v8, v9
	v_cvt_pk_bf16_f32 v29, v10, v11
	v_cvt_pk_bf16_f32 v30, v12, v13
	v_cvt_pk_bf16_f32 v31, v14, v15
	global_store_dwordx4 v1, v[28:31], s[58:59]
	s_add_u32 s58, s58, s60
	s_addc_u32 s59, s59, s61
	v_lshlrev_b32_e32 v16, 16, v36
	v_and_b32_e32 v17, 0xffff0000, v36
	v_lshlrev_b32_e32 v18, 16, v37
	v_and_b32_e32 v19, 0xffff0000, v37
	v_lshlrev_b32_e32 v20, 16, v38
	v_and_b32_e32 v21, 0xffff0000, v38
	v_lshlrev_b32_e32 v22, 16, v39
	v_and_b32_e32 v23, 0xffff0000, v39
	v_fma_f32 v8, v8, v72, v16
	v_fma_f32 v9, v9, v72, v17
	v_fma_f32 v10, v10, v72, v18
	v_fma_f32 v11, v11, v72, v19
	v_fma_f32 v12, v12, v72, v20
	v_fma_f32 v13, v13, v72, v21
	v_fma_f32 v14, v14, v72, v22
	v_fma_f32 v15, v15, v72, v23
	s_waitcnt vmcnt(20)
	v_cvt_pk_bf16_f32 v24, v8, v9
	v_cvt_pk_bf16_f32 v25, v10, v11
	v_cvt_pk_bf16_f32 v26, v12, v13
	v_cvt_pk_bf16_f32 v27, v14, v15
	global_store_dwordx4 v1, v[24:27], s[58:59]
	s_add_u32 s58, s58, s60
	s_addc_u32 s59, s59, s61
	v_lshlrev_b32_e32 v16, 16, v40
	v_and_b32_e32 v17, 0xffff0000, v40
	v_lshlrev_b32_e32 v18, 16, v41
	v_and_b32_e32 v19, 0xffff0000, v41
	v_lshlrev_b32_e32 v20, 16, v42
	v_and_b32_e32 v21, 0xffff0000, v42
	v_lshlrev_b32_e32 v22, 16, v43
	v_and_b32_e32 v23, 0xffff0000, v43
	v_fma_f32 v8, v8, v80, v16
	v_fma_f32 v9, v9, v80, v17
	v_fma_f32 v10, v10, v80, v18
	v_fma_f32 v11, v11, v80, v19
	v_fma_f32 v12, v12, v80, v20
	v_fma_f32 v13, v13, v80, v21
	v_fma_f32 v14, v14, v80, v22
	v_fma_f32 v15, v15, v80, v23
	s_waitcnt vmcnt(19)
	v_cvt_pk_bf16_f32 v28, v8, v9
	v_cvt_pk_bf16_f32 v29, v10, v11
	v_cvt_pk_bf16_f32 v30, v12, v13
	v_cvt_pk_bf16_f32 v31, v14, v15
	global_store_dwordx4 v1, v[28:31], s[58:59]
	s_add_u32 s58, s58, s60
	s_addc_u32 s59, s59, s61
	v_lshlrev_b32_e32 v16, 16, v44
	v_and_b32_e32 v17, 0xffff0000, v44
	v_lshlrev_b32_e32 v18, 16, v45
	v_and_b32_e32 v19, 0xffff0000, v45
	v_lshlrev_b32_e32 v20, 16, v46
	v_and_b32_e32 v21, 0xffff0000, v46
	v_lshlrev_b32_e32 v22, 16, v47
	v_and_b32_e32 v23, 0xffff0000, v47
	v_fma_f32 v8, v8, v96, v16
	v_fma_f32 v9, v9, v96, v17
	v_fma_f32 v10, v10, v96, v18
	v_fma_f32 v11, v11, v96, v19
	v_fma_f32 v12, v12, v96, v20
	v_fma_f32 v13, v13, v96, v21
	v_fma_f32 v14, v14, v96, v22
	v_fma_f32 v15, v15, v96, v23
	s_mov_b64 s[58:59], s[64:65]
	s_mov_b32 s68, 4
; __device__ __forceinline__ unsigned pk2(float lo, float hi) { const f32x2cv v = {lo, hi}; const bf16x2cv b = __builtin_convertvector(v, bf16x2cv); return __builtin_bit_cast(unsigned, b); }
; __global__ void __launch_bounds__(NT, 2) fwd_kernel(Args args) {
;     ...
;             _Pragma("unroll 1") for (int st = 0; st < 72; st += 8) {
;                 v2u loc[8]; float dec[8]; bf16* ad[8];
; #pragma unroll
;                 for (int u = 0; u < 8; ++u) { const int ch = chain_chunk(b, d, (st + u < 68) ? st + u : 67); ad[u] = STS + (size_t)((ch * 8 + hh) * 2 + d) * 4096 + e; loc[u] = *(const v2u*)ad[u];
;                     dec[u] = DECS[(size_t)(ch * 2 + d) * 8 + hh]; }
; #pragma unroll
;                 for (int u = 0; u < 8; ++u) { if (st + u >= 68) break; v2u o; o.x = pk2(s0, s1); o.y = pk2(s2, s3); *(v2u*)ad[u] = o;
;                     s0 = s0 * dec[u] + bflo(loc[u].x); s1 = s1 * dec[u] + bfhi(loc[u].x); s2 = s2 * dec[u] + bflo(loc[u].y); s3 = s3 * dec[u] + bfhi(loc[u].y); }
.Lp5_ssd_loop:
	global_load_dwordx4 v[32:35], v1, s[54:55] nt
	global_load_dword v64, v3, s[56:57]
	s_add_u32 s54, s54, s60
	s_addc_u32 s55, s55, s61
	s_add_u32 s56, s56, s62
	s_addc_u32 s57, s57, s63
	global_load_dwordx4 v[36:39], v1, s[54:55] nt
	global_load_dword v72, v3, s[56:57]
	s_add_u32 s54, s54, s60
	s_addc_u32 s55, s55, s61
	s_add_u32 s56, s56, s62
	s_addc_u32 s57, s57, s63
	global_load_dwordx4 v[40:43], v1, s[54:55] nt
	global_load_dword v80, v3, s[56:57]
	s_add_u32 s54, s54, s60
	s_addc_u32 s55, s55, s61
	s_add_u32 s56, s56, s62
	s_addc_u32 s57, s57, s63
	global_load_dwordx4 v[44:47], v1, s[54:55] nt
	global_load_dword v96, v3, s[56:57]
	s_add_u32 s54, s54, s60
	s_addc_u32 s55, s55, s61
	s_add_u32 s56, s56, s62
	s_addc_u32 s57, s57, s63
	global_load_dwordx4 v[48:51], v1, s[54:55] nt
	global_load_dword v104, v3, s[56:57]
	s_add_u32 s54, s54, s60
	s_addc_u32 s55, s55, s61
	s_add_u32 s56, s56, s62
	s_addc_u32 s57, s57, s63
	global_load_dwordx4 v[52:55], v1, s[54:55] nt
	global_load_dword v112, v3, s[56:57]
	s_add_u32 s54, s54, s60
	s_addc_u32 s55, s55, s61
	s_add_u32 s56, s56, s62
	s_addc_u32 s57, s57, s63
	global_load_dwordx4 v[56:59], v1, s[54:55] nt
	global_load_dword v120, v3, s[56:57]
	s_add_u32 s54, s54, s60
	s_addc_u32 s55, s55, s61
	s_add_u32 s56, s56, s62
	s_addc_u32 s57, s57, s63
	global_load_dwordx4 v[60:63], v1, s[54:55] nt
	global_load_dword v128, v3, s[56:57]
	s_add_u32 s54, s54, s60
	s_addc_u32 s55, s55, s61
	s_add_u32 s56, s56, s62
	s_addc_u32 s57, s57, s63
	s_waitcnt vmcnt(34)
	v_cvt_pk_bf16_f32 v24, v8, v9
	v_cvt_pk_bf16_f32 v25, v10, v11
	v_cvt_pk_bf16_f32 v26, v12, v13
	v_cvt_pk_bf16_f32 v27, v14, v15
	global_store_dwordx4 v1, v[24:27], s[58:59]
	s_add_u32 s58, s58, s60
	s_addc_u32 s59, s59, s61
	v_lshlrev_b32_e32 v16, 16, v136
	v_and_b32_e32 v17, 0xffff0000, v136
	v_lshlrev_b32_e32 v18, 16, v137
	v_and_b32_e32 v19, 0xffff0000, v137
	v_lshlrev_b32_e32 v20, 16, v138
	v_and_b32_e32 v21, 0xffff0000, v138
	v_lshlrev_b32_e32 v22, 16, v139
	v_and_b32_e32 v23, 0xffff0000, v139
	v_fma_f32 v8, v8, v168, v16
	v_fma_f32 v9, v9, v168, v17
	v_fma_f32 v10, v10, v168, v18
	v_fma_f32 v11, v11, v168, v19
	v_fma_f32 v12, v12, v168, v20
	v_fma_f32 v13, v13, v168, v21
	v_fma_f32 v14, v14, v168, v22
	v_fma_f32 v15, v15, v168, v23
	s_waitcnt vmcnt(33)
	v_cvt_pk_bf16_f32 v28, v8, v9
	v_cvt_pk_bf16_f32 v29, v10, v11
	v_cvt_pk_bf16_f32 v30, v12, v13
	v_cvt_pk_bf16_f32 v31, v14, v15
	global_store_dwordx4 v1, v[28:31], s[58:59]
	s_add_u32 s58, s58, s60
	s_addc_u32 s59, s59, s61
	v_lshlrev_b32_e32 v16, 16, v140
	v_and_b32_e32 v17, 0xffff0000, v140
	v_lshlrev_b32_e32 v18, 16, v141
	v_and_b32_e32 v19, 0xffff0000, v141
	v_lshlrev_b32_e32 v20, 16, v142
	v_and_b32_e32 v21, 0xffff0000, v142
	v_lshlrev_b32_e32 v22, 16, v143
	v_and_b32_e32 v23, 0xffff0000, v143
	v_fma_f32 v8, v8, v176, v16
	v_fma_f32 v9, v9, v176, v17
	v_fma_f32 v10, v10, v176, v18
	v_fma_f32 v11, v11, v176, v19
	v_fma_f32 v12, v12, v176, v20
	v_fma_f32 v13, v13, v176, v21
	v_fma_f32 v14, v14, v176, v22
	v_fma_f32 v15, v15, v176, v23
	s_waitcnt vmcnt(32)
	v_cvt_pk_bf16_f32 v24, v8, v9
	v_cvt_pk_bf16_f32 v25, v10, v11
	v_cvt_pk_bf16_f32 v26, v12, v13
	v_cvt_pk_bf16_f32 v27, v14, v15
	global_store_dwordx4 v1, v[24:27], s[58:59]
	s_add_u32 s58, s58, s60
	s_addc_u32 s59, s59, s61
	v_lshlrev_b32_e32 v16, 16, v144
	v_and_b32_e32 v17, 0xffff0000, v144
	v_lshlrev_b32_e32 v18, 16, v145
	v_and_b32_e32 v19, 0xffff0000, v145
	v_lshlrev_b32_e32 v20, 16, v146
	v_and_b32_e32 v21, 0xffff0000, v146
	v_lshlrev_b32_e32 v22, 16, v147
	v_and_b32_e32 v23, 0xffff0000, v147
	v_fma_f32 v8, v8, v184, v16
	v_fma_f32 v9, v9, v184, v17
	v_fma_f32 v10, v10, v184, v18
	v_fma_f32 v11, v11, v184, v19
	v_fma_f32 v12, v12, v184, v20
	v_fma_f32 v13, v13, v184, v21
	v_fma_f32 v14, v14, v184, v22
	v_fma_f32 v15, v15, v184, v23
	s_waitcnt vmcnt(31)
	v_cvt_pk_bf16_f32 v28, v8, v9
	v_cvt_pk_bf16_f32 v29, v10, v11
	v_cvt_pk_bf16_f32 v30, v12, v13
	v_cvt_pk_bf16_f32 v31, v14, v15
	global_store_dwordx4 v1, v[28:31], s[58:59]
	s_add_u32 s58, s58, s60
	s_addc_u32 s59, s59, s61
	v_lshlrev_b32_e32 v16, 16, v148
	v_and_b32_e32 v17, 0xffff0000, v148
	v_lshlrev_b32_e32 v18, 16, v149
	v_and_b32_e32 v19, 0xffff0000, v149
	v_lshlrev_b32_e32 v20, 16, v150
	v_and_b32_e32 v21, 0xffff0000, v150
	v_lshlrev_b32_e32 v22, 16, v151
	v_and_b32_e32 v23, 0xffff0000, v151
	v_fma_f32 v8, v8, v192, v16
	v_fma_f32 v9, v9, v192, v17
	v_fma_f32 v10, v10, v192, v18
	v_fma_f32 v11, v11, v192, v19
	v_fma_f32 v12, v12, v192, v20
	v_fma_f32 v13, v13, v192, v21
	v_fma_f32 v14, v14, v192, v22
	v_fma_f32 v15, v15, v192, v23
	s_waitcnt vmcnt(30)
	v_cvt_pk_bf16_f32 v24, v8, v9
	v_cvt_pk_bf16_f32 v25, v10, v11
	v_cvt_pk_bf16_f32 v26, v12, v13
	v_cvt_pk_bf16_f32 v27, v14, v15
	global_store_dwordx4 v1, v[24:27], s[58:59]
	s_add_u32 s58, s58, s60
	s_addc_u32 s59, s59, s61
	v_lshlrev_b32_e32 v16, 16, v152
	v_and_b32_e32 v17, 0xffff0000, v152
	v_lshlrev_b32_e32 v18, 16, v153
	v_and_b32_e32 v19, 0xffff0000, v153
	v_lshlrev_b32_e32 v20, 16, v154
	v_and_b32_e32 v21, 0xffff0000, v154
	v_lshlrev_b32_e32 v22, 16, v155
	v_and_b32_e32 v23, 0xffff0000, v155
	v_fma_f32 v8, v8, v200, v16
	v_fma_f32 v9, v9, v200, v17
	v_fma_f32 v10, v10, v200, v18
	v_fma_f32 v11, v11, v200, v19
	v_fma_f32 v12, v12, v200, v20
	v_fma_f32 v13, v13, v200, v21
	v_fma_f32 v14, v14, v200, v22
	v_fma_f32 v15, v15, v200, v23
	s_waitcnt vmcnt(29)
; __device__ __forceinline__ unsigned pk2(float lo, float hi) { const f32x2cv v = {lo, hi}; const bf16x2cv b = __builtin_convertvector(v, bf16x2cv); return __builtin_bit_cast(unsigned, b); }
; __global__ void __launch_bounds__(NT, 2) fwd_kernel(Args args) {
;     ...
;             _Pragma("unroll 1") for (int st = 0; st < 72; st += 8) {
;                 v2u loc[8]; float dec[8]; bf16* ad[8];
; #pragma unroll
;                 for (int u = 0; u < 8; ++u) { const int ch = chain_chunk(b, d, (st + u < 68) ? st + u : 67); ad[u] = STS + (size_t)((ch * 8 + hh) * 2 + d) * 4096 + e; loc[u] = *(const v2u*)ad[u];
;                     dec[u] = DECS[(size_t)(ch * 2 + d) * 8 + hh]; }
; #pragma unroll
;                 for (int u = 0; u < 8; ++u) { if (st + u >= 68) break; v2u o; o.x = pk2(s0, s1); o.y = pk2(s2, s3); *(v2u*)ad[u] = o;
;                     s0 = s0 * dec[u] + bflo(loc[u].x); s1 = s1 * dec[u] + bfhi(loc[u].x); s2 = s2 * dec[u] + bflo(loc[u].y); s3 = s3 * dec[u] + bfhi(loc[u].y); }
	v_cvt_pk_bf16_f32 v28, v8, v9
	v_cvt_pk_bf16_f32 v29, v10, v11
	v_cvt_pk_bf16_f32 v30, v12, v13
	v_cvt_pk_bf16_f32 v31, v14, v15
	global_store_dwordx4 v1, v[28:31], s[58:59]
	s_add_u32 s58, s58, s60
	s_addc_u32 s59, s59, s61
	v_lshlrev_b32_e32 v16, 16, v156
	v_and_b32_e32 v17, 0xffff0000, v156
	v_lshlrev_b32_e32 v18, 16, v157
	v_and_b32_e32 v19, 0xffff0000, v157
	v_lshlrev_b32_e32 v20, 16, v158
	v_and_b32_e32 v21, 0xffff0000, v158
	v_lshlrev_b32_e32 v22, 16, v159
	v_and_b32_e32 v23, 0xffff0000, v159
	v_fma_f32 v8, v8, v208, v16
	v_fma_f32 v9, v9, v208, v17
	v_fma_f32 v10, v10, v208, v18
	v_fma_f32 v11, v11, v208, v19
	v_fma_f32 v12, v12, v208, v20
	v_fma_f32 v13, v13, v208, v21
	v_fma_f32 v14, v14, v208, v22
	v_fma_f32 v15, v15, v208, v23
	s_waitcnt vmcnt(28)
	v_cvt_pk_bf16_f32 v24, v8, v9
	v_cvt_pk_bf16_f32 v25, v10, v11
	v_cvt_pk_bf16_f32 v26, v12, v13
	v_cvt_pk_bf16_f32 v27, v14, v15
	global_store_dwordx4 v1, v[24:27], s[58:59]
	s_add_u32 s58, s58, s60
	s_addc_u32 s59, s59, s61
	v_lshlrev_b32_e32 v16, 16, v160
	v_and_b32_e32 v17, 0xffff0000, v160
	v_lshlrev_b32_e32 v18, 16, v161
	v_and_b32_e32 v19, 0xffff0000, v161
	v_lshlrev_b32_e32 v20, 16, v162
	v_and_b32_e32 v21, 0xffff0000, v162
	v_lshlrev_b32_e32 v22, 16, v163
	v_and_b32_e32 v23, 0xffff0000, v163
	v_fma_f32 v8, v8, v216, v16
	v_fma_f32 v9, v9, v216, v17
	v_fma_f32 v10, v10, v216, v18
	v_fma_f32 v11, v11, v216, v19
	v_fma_f32 v12, v12, v216, v20
	v_fma_f32 v13, v13, v216, v21
	v_fma_f32 v14, v14, v216, v22
	v_fma_f32 v15, v15, v216, v23
	s_waitcnt vmcnt(27)
	v_cvt_pk_bf16_f32 v28, v8, v9
	v_cvt_pk_bf16_f32 v29, v10, v11
	v_cvt_pk_bf16_f32 v30, v12, v13
	v_cvt_pk_bf16_f32 v31, v14, v15
	global_store_dwordx4 v1, v[28:31], s[58:59]
	s_add_u32 s58, s58, s60
	s_addc_u32 s59, s59, s61
	v_lshlrev_b32_e32 v16, 16, v164
	v_and_b32_e32 v17, 0xffff0000, v164
	v_lshlrev_b32_e32 v18, 16, v165
	v_and_b32_e32 v19, 0xffff0000, v165
	v_lshlrev_b32_e32 v20, 16, v166
	v_and_b32_e32 v21, 0xffff0000, v166
	v_lshlrev_b32_e32 v22, 16, v167
	v_and_b32_e32 v23, 0xffff0000, v167
	v_fma_f32 v8, v8, v224, v16
	v_fma_f32 v9, v9, v224, v17
	v_fma_f32 v10, v10, v224, v18
	v_fma_f32 v11, v11, v224, v19
	v_fma_f32 v12, v12, v224, v20
	v_fma_f32 v13, v13, v224, v21
	v_fma_f32 v14, v14, v224, v22
	v_fma_f32 v15, v15, v224, v23
	global_load_dwordx4 v[136:139], v1, s[54:55] nt
	global_load_dword v168, v3, s[56:57]
	s_add_u32 s54, s54, s60
	s_addc_u32 s55, s55, s61
	s_add_u32 s56, s56, s62
	s_addc_u32 s57, s57, s63
	global_load_dwordx4 v[140:143], v1, s[54:55] nt
	global_load_dword v176, v3, s[56:57]
	s_add_u32 s54, s54, s60
	s_addc_u32 s55, s55, s61
	s_add_u32 s56, s56, s62
	s_addc_u32 s57, s57, s63
	global_load_dwordx4 v[144:147], v1, s[54:55] nt
	global_load_dword v184, v3, s[56:57]
	s_add_u32 s54, s54, s60
	s_addc_u32 s55, s55, s61
	s_add_u32 s56, s56, s62
	s_addc_u32 s57, s57, s63
	global_load_dwordx4 v[148:151], v1, s[54:55] nt
	global_load_dword v192, v3, s[56:57]
	s_add_u32 s54, s54, s60
	s_addc_u32 s55, s55, s61
	s_add_u32 s56, s56, s62
	s_addc_u32 s57, s57, s63
	global_load_dwordx4 v[152:155], v1, s[54:55] nt
	global_load_dword v200, v3, s[56:57]
	s_add_u32 s54, s54, s60
	s_addc_u32 s55, s55, s61
	s_add_u32 s56, s56, s62
	s_addc_u32 s57, s57, s63
	global_load_dwordx4 v[156:159], v1, s[54:55] nt
	global_load_dword v208, v3, s[56:57]
	s_add_u32 s54, s54, s60
	s_addc_u32 s55, s55, s61
	s_add_u32 s56, s56, s62
	s_addc_u32 s57, s57, s63
	global_load_dwordx4 v[160:163], v1, s[54:55] nt
	global_load_dword v216, v3, s[56:57]
	s_add_u32 s54, s54, s60
	s_addc_u32 s55, s55, s61
	s_add_u32 s56, s56, s62
	s_addc_u32 s57, s57, s63
	global_load_dwordx4 v[164:167], v1, s[54:55] nt
	global_load_dword v224, v3, s[56:57]
	s_add_u32 s54, s54, s60
	s_addc_u32 s55, s55, s61
	s_add_u32 s56, s56, s62
	s_addc_u32 s57, s57, s63
	s_waitcnt vmcnt(34)
	v_cvt_pk_bf16_f32 v24, v8, v9
	v_cvt_pk_bf16_f32 v25, v10, v11
	v_cvt_pk_bf16_f32 v26, v12, v13
	v_cvt_pk_bf16_f32 v27, v14, v15
	global_store_dwordx4 v1, v[24:27], s[58:59]
	s_add_u32 s58, s58, s60
	s_addc_u32 s59, s59, s61
	v_lshlrev_b32_e32 v16, 16, v32
	v_and_b32_e32 v17, 0xffff0000, v32
	v_lshlrev_b32_e32 v18, 16, v33
	v_and_b32_e32 v19, 0xffff0000, v33
	v_lshlrev_b32_e32 v20, 16, v34
	v_and_b32_e32 v21, 0xffff0000, v34
	v_lshlrev_b32_e32 v22, 16, v35
	v_and_b32_e32 v23, 0xffff0000, v35
	v_fma_f32 v8, v8, v64, v16
	v_fma_f32 v9, v9, v64, v17
	v_fma_f32 v10, v10, v64, v18
	v_fma_f32 v11, v11, v64, v19
	v_fma_f32 v12, v12, v64, v20
	v_fma_f32 v13, v13, v64, v21
	v_fma_f32 v14, v14, v64, v22
	v_fma_f32 v15, v15, v64, v23
	s_waitcnt vmcnt(33)
	v_cvt_pk_bf16_f32 v28, v8, v9
	v_cvt_pk_bf16_f32 v29, v10, v11
	v_cvt_pk_bf16_f32 v30, v12, v13
	v_cvt_pk_bf16_f32 v31, v14, v15
	global_store_dwordx4 v1, v[28:31], s[58:59]
	s_add_u32 s58, s58, s60
	s_addc_u32 s59, s59, s61
	v_lshlrev_b32_e32 v16, 16, v36
	v_and_b32_e32 v17, 0xffff0000, v36
	v_lshlrev_b32_e32 v18, 16, v37
	v_and_b32_e32 v19, 0xffff0000, v37
	v_lshlrev_b32_e32 v20, 16, v38
	v_and_b32_e32 v21, 0xffff0000, v38
	v_lshlrev_b32_e32 v22, 16, v39
	v_and_b32_e32 v23, 0xffff0000, v39
	v_fma_f32 v8, v8, v72, v16
	v_fma_f32 v9, v9, v72, v17
	v_fma_f32 v10, v10, v72, v18
	v_fma_f32 v11, v11, v72, v19
	v_fma_f32 v12, v12, v72, v20
	v_fma_f32 v13, v13, v72, v21
	v_fma_f32 v14, v14, v72, v22
	v_fma_f32 v15, v15, v72, v23
	s_waitcnt vmcnt(32)
; __device__ __forceinline__ unsigned pk2(float lo, float hi) { const f32x2cv v = {lo, hi}; const bf16x2cv b = __builtin_convertvector(v, bf16x2cv); return __builtin_bit_cast(unsigned, b); }
; __global__ void __launch_bounds__(NT, 2) fwd_kernel(Args args) {
;     ...
;             _Pragma("unroll 1") for (int st = 0; st < 72; st += 8) {
;                 v2u loc[8]; float dec[8]; bf16* ad[8];
; #pragma unroll
;                 for (int u = 0; u < 8; ++u) { const int ch = chain_chunk(b, d, (st + u < 68) ? st + u : 67); ad[u] = STS + (size_t)((ch * 8 + hh) * 2 + d) * 4096 + e; loc[u] = *(const v2u*)ad[u];
;                     dec[u] = DECS[(size_t)(ch * 2 + d) * 8 + hh]; }
; #pragma unroll
;                 for (int u = 0; u < 8; ++u) { if (st + u >= 68) break; v2u o; o.x = pk2(s0, s1); o.y = pk2(s2, s3); *(v2u*)ad[u] = o;
;                     s0 = s0 * dec[u] + bflo(loc[u].x); s1 = s1 * dec[u] + bfhi(loc[u].x); s2 = s2 * dec[u] + bflo(loc[u].y); s3 = s3 * dec[u] + bfhi(loc[u].y); }
	v_cvt_pk_bf16_f32 v24, v8, v9
	v_cvt_pk_bf16_f32 v25, v10, v11
	v_cvt_pk_bf16_f32 v26, v12, v13
	v_cvt_pk_bf16_f32 v27, v14, v15
	global_store_dwordx4 v1, v[24:27], s[58:59]
	s_add_u32 s58, s58, s60
	s_addc_u32 s59, s59, s61
	v_lshlrev_b32_e32 v16, 16, v40
	v_and_b32_e32 v17, 0xffff0000, v40
	v_lshlrev_b32_e32 v18, 16, v41
	v_and_b32_e32 v19, 0xffff0000, v41
	v_lshlrev_b32_e32 v20, 16, v42
	v_and_b32_e32 v21, 0xffff0000, v42
	v_lshlrev_b32_e32 v22, 16, v43
	v_and_b32_e32 v23, 0xffff0000, v43
	v_fma_f32 v8, v8, v80, v16
	v_fma_f32 v9, v9, v80, v17
	v_fma_f32 v10, v10, v80, v18
	v_fma_f32 v11, v11, v80, v19
	v_fma_f32 v12, v12, v80, v20
	v_fma_f32 v13, v13, v80, v21
	v_fma_f32 v14, v14, v80, v22
	v_fma_f32 v15, v15, v80, v23
	s_waitcnt vmcnt(31)
	v_cvt_pk_bf16_f32 v28, v8, v9
	v_cvt_pk_bf16_f32 v29, v10, v11
	v_cvt_pk_bf16_f32 v30, v12, v13
	v_cvt_pk_bf16_f32 v31, v14, v15
	global_store_dwordx4 v1, v[28:31], s[58:59]
	s_add_u32 s58, s58, s60
	s_addc_u32 s59, s59, s61
	v_lshlrev_b32_e32 v16, 16, v44
	v_and_b32_e32 v17, 0xffff0000, v44
	v_lshlrev_b32_e32 v18, 16, v45
	v_and_b32_e32 v19, 0xffff0000, v45
	v_lshlrev_b32_e32 v20, 16, v46
	v_and_b32_e32 v21, 0xffff0000, v46
	v_lshlrev_b32_e32 v22, 16, v47
	v_and_b32_e32 v23, 0xffff0000, v47
	v_fma_f32 v8, v8, v96, v16
	v_fma_f32 v9, v9, v96, v17
	v_fma_f32 v10, v10, v96, v18
	v_fma_f32 v11, v11, v96, v19
	v_fma_f32 v12, v12, v96, v20
	v_fma_f32 v13, v13, v96, v21
	v_fma_f32 v14, v14, v96, v22
	v_fma_f32 v15, v15, v96, v23
	s_waitcnt vmcnt(30)
	v_cvt_pk_bf16_f32 v24, v8, v9
	v_cvt_pk_bf16_f32 v25, v10, v11
	v_cvt_pk_bf16_f32 v26, v12, v13
	v_cvt_pk_bf16_f32 v27, v14, v15
	global_store_dwordx4 v1, v[24:27], s[58:59]
	s_add_u32 s58, s58, s60
	s_addc_u32 s59, s59, s61
	v_lshlrev_b32_e32 v16, 16, v48
	v_and_b32_e32 v17, 0xffff0000, v48
	v_lshlrev_b32_e32 v18, 16, v49
	v_and_b32_e32 v19, 0xffff0000, v49
	v_lshlrev_b32_e32 v20, 16, v50
	v_and_b32_e32 v21, 0xffff0000, v50
	v_lshlrev_b32_e32 v22, 16, v51
	v_and_b32_e32 v23, 0xffff0000, v51
	v_fma_f32 v8, v8, v104, v16
	v_fma_f32 v9, v9, v104, v17
	v_fma_f32 v10, v10, v104, v18
	v_fma_f32 v11, v11, v104, v19
	v_fma_f32 v12, v12, v104, v20
	v_fma_f32 v13, v13, v104, v21
	v_fma_f32 v14, v14, v104, v22
	v_fma_f32 v15, v15, v104, v23
	s_waitcnt vmcnt(29)
	v_cvt_pk_bf16_f32 v28, v8, v9
	v_cvt_pk_bf16_f32 v29, v10, v11
	v_cvt_pk_bf16_f32 v30, v12, v13
	v_cvt_pk_bf16_f32 v31, v14, v15
	global_store_dwordx4 v1, v[28:31], s[58:59]
	s_add_u32 s58, s58, s60
	s_addc_u32 s59, s59, s61
	v_lshlrev_b32_e32 v16, 16, v52
	v_and_b32_e32 v17, 0xffff0000, v52
	v_lshlrev_b32_e32 v18, 16, v53
	v_and_b32_e32 v19, 0xffff0000, v53
	v_lshlrev_b32_e32 v20, 16, v54
	v_and_b32_e32 v21, 0xffff0000, v54
	v_lshlrev_b32_e32 v22, 16, v55
	v_and_b32_e32 v23, 0xffff0000, v55
	v_fma_f32 v8, v8, v112, v16
	v_fma_f32 v9, v9, v112, v17
	v_fma_f32 v10, v10, v112, v18
	v_fma_f32 v11, v11, v112, v19
	v_fma_f32 v12, v12, v112, v20
	v_fma_f32 v13, v13, v112, v21
	v_fma_f32 v14, v14, v112, v22
	v_fma_f32 v15, v15, v112, v23
	s_waitcnt vmcnt(28)
	v_cvt_pk_bf16_f32 v24, v8, v9
	v_cvt_pk_bf16_f32 v25, v10, v11
	v_cvt_pk_bf16_f32 v26, v12, v13
	v_cvt_pk_bf16_f32 v27, v14, v15
	global_store_dwordx4 v1, v[24:27], s[58:59]
	s_add_u32 s58, s58, s60
	s_addc_u32 s59, s59, s61
	v_lshlrev_b32_e32 v16, 16, v56
	v_and_b32_e32 v17, 0xffff0000, v56
	v_lshlrev_b32_e32 v18, 16, v57
	v_and_b32_e32 v19, 0xffff0000, v57
	v_lshlrev_b32_e32 v20, 16, v58
	v_and_b32_e32 v21, 0xffff0000, v58
	v_lshlrev_b32_e32 v22, 16, v59
	v_and_b32_e32 v23, 0xffff0000, v59
	v_fma_f32 v8, v8, v120, v16
	v_fma_f32 v9, v9, v120, v17
	v_fma_f32 v10, v10, v120, v18
	v_fma_f32 v11, v11, v120, v19
	v_fma_f32 v12, v12, v120, v20
	v_fma_f32 v13, v13, v120, v21
	v_fma_f32 v14, v14, v120, v22
	v_fma_f32 v15, v15, v120, v23
	s_waitcnt vmcnt(27)
	v_cvt_pk_bf16_f32 v28, v8, v9
	v_cvt_pk_bf16_f32 v29, v10, v11
	v_cvt_pk_bf16_f32 v30, v12, v13
	v_cvt_pk_bf16_f32 v31, v14, v15
	global_store_dwordx4 v1, v[28:31], s[58:59]
	s_add_u32 s58, s58, s60
	s_addc_u32 s59, s59, s61
	v_lshlrev_b32_e32 v16, 16, v60
	v_and_b32_e32 v17, 0xffff0000, v60
	v_lshlrev_b32_e32 v18, 16, v61
	v_and_b32_e32 v19, 0xffff0000, v61
	v_lshlrev_b32_e32 v20, 16, v62
	v_and_b32_e32 v21, 0xffff0000, v62
	v_lshlrev_b32_e32 v22, 16, v63
	v_and_b32_e32 v23, 0xffff0000, v63
	v_fma_f32 v8, v8, v128, v16
	v_fma_f32 v9, v9, v128, v17
	v_fma_f32 v10, v10, v128, v18
	v_fma_f32 v11, v11, v128, v19
	v_fma_f32 v12, v12, v128, v20
	v_fma_f32 v13, v13, v128, v21
	v_fma_f32 v14, v14, v128, v22
	v_fma_f32 v15, v15, v128, v23
	s_sub_u32 s68, s68, 1
	s_cmp_lg_u32 s68, 0
	s_cbranch_scc1 .Lp5_ssd_loop
	s_branch .LBB0_705
